# retention: step-A MFMA loops fully unrolled with 4-deep pipelined LDS operand reads; prefetch loads as global_load
# speedup vs baseline: 1.0117x; 1.0117x over previous
; #define LAS __attribute__((address_space(3)))
; __device__ __forceinline__ void ret_mfma(const Params& P, LAS unsigned char* lds, int wave) {
;     ...
;             for (int i = 0; i < 4; ++i) { const int id = t + 512 * i, r = id >> 5, ch = id & 31;
;                 *(LAS u32x4*)(lds + Q_OFF + r * QP + ch * 16) = pq[i]; *(LAS u32x4*)(lds + K_OFF + r * QP + ch * 16) = pkk[i]; }
;             *(LAS u32x4*)(lds + V_OFF + vr * VP + vc * 16) = pvv;
;             __syncthreads();
;             if (c + 1 < 64) { const size_t r1 = rb + (size_t)(c + 1) * 64;
; #pragma unroll
;                 for (int i = 0; i < 4; ++i) { const int id = t + 512 * i, r = id >> 5, ch = id & 31;
;                     pq[i] = *(const u32x4*)(QK + (r1 + r) * 2048 + hh * 256 + ch * 8); pkk[i] = *(const u32x4*)(QK + (r1 + r) * 2048 + 1024 + hh * 256 + ch * 8); }
;                 pvv = *(const u32x4*)(V + (r1 + vr) * 2048 + hh * 512 + slice * 64 + vc * 8); }
;     ...
;                 const int w4 = wave - 4, dvblk = w4 >> 1, nblk = w4 & 1, n = nblk * 32 + q32;
; #pragma unroll 4
;                 for (int ks = 0; ks < 16; ++ks) {
;                     const bf16x8 a = *(const LAS bf16x8*)(lds + ST_OFF + (dvblk * 32 + q32) * QP + ks * 32 + hf * 16);
;                     const bf16x8 bq = *(const LAS bf16x8*)(lds + Q_OFF + n * QP + ks * 32 + hf * 16);
;                     acc = __builtin_amdgcn_mfma_f32_32x32x16_bf16(a, bq, acc, 0, 0, 0);
;                 }
;                 acc = acc * dec[0];
;             }
.LBB0_255:
	s_add_i32 s14, s29, 1
	s_cmp_lg_u32 s29, 63
	s_waitcnt lgkmcnt(0)
	ds_write_b128 v173, v[48:51]
	ds_write_b128 v173, v[52:55] offset:33792
	ds_write_b128 v174, v[56:59]
	ds_write_b128 v174, v[60:63] offset:33792
	ds_write_b128 v175, v[64:67]
	ds_write_b128 v175, v[68:71] offset:33792
	ds_write_b128 v176, v[72:75]
	ds_write_b128 v176, v[76:79] offset:33792
	ds_write_b128 v177, v[80:83]
	s_waitcnt lgkmcnt(0)
	s_barrier
	s_cbranch_scc0 .LBB0_257
	s_lshl_b32 s8, s14, 6
	s_add_u32 s8, s18, s8
	s_addc_u32 s9, s19, 0
	v_lshl_add_u64 v[32:33], s[8:9], 0, v[92:93]
	v_lshlrev_b64 v[32:33], 12, v[32:33]
	v_lshl_add_u64 v[32:33], v[144:145], 0, v[32:33]
	global_load_dwordx4 v[48:51], v[32:33], off
	global_load_dwordx4 v[52:55], v[32:33], off offset:2048
	v_lshl_add_u64 v[32:33], s[8:9], 0, v[94:95]
	v_lshlrev_b64 v[32:33], 12, v[32:33]
	v_lshl_add_u64 v[32:33], v[144:145], 0, v[32:33]
	global_load_dwordx4 v[56:59], v[32:33], off
	global_load_dwordx4 v[60:63], v[32:33], off offset:2048
	v_lshl_add_u64 v[32:33], s[8:9], 0, v[96:97]
	v_lshlrev_b64 v[32:33], 12, v[32:33]
	v_lshl_add_u64 v[32:33], v[144:145], 0, v[32:33]
	global_load_dwordx4 v[64:67], v[32:33], off
	global_load_dwordx4 v[68:71], v[32:33], off offset:2048
	v_lshl_add_u64 v[32:33], s[8:9], 0, v[98:99]
	v_lshlrev_b64 v[32:33], 12, v[32:33]
	v_lshl_add_u64 v[32:33], v[144:145], 0, v[32:33]
	global_load_dwordx4 v[72:75], v[32:33], off
	global_load_dwordx4 v[76:79], v[32:33], off offset:2048
	v_lshl_add_u64 v[32:33], s[8:9], 0, v[88:89]
	v_lshlrev_b64 v[32:33], 12, v[32:33]
	v_lshl_add_u64 v[32:33], v[124:125], 0, v[32:33]
	global_load_dwordx4 v[80:83], v[32:33], off
.LBB0_257:
	v_cndmask_b32_e64 v32, 0, 1, s[10:11]
	v_cmp_ne_u32_e64 s[8:9], 1, v32
	s_andn2_b64 vcc, exec, s[10:11]
	s_mov_b64 s[22:23], -1
	s_cbranch_vccnz .LBB0_261
	ds_read_b128 v[190:193], v171
	ds_read_b128 v[194:197], v150
	ds_read_b128 v[198:201], v171 offset:32
	ds_read_b128 v[202:205], v150 offset:32
	ds_read_b128 v[210:213], v171 offset:64
	ds_read_b128 v[214:217], v150 offset:64
	ds_read_b128 v[218:221], v171 offset:96
	ds_read_b128 v[222:225], v150 offset:96
	s_waitcnt lgkmcnt(6)
	v_mfma_f32_32x32x16_bf16 v[32:47], v[190:193], v[194:197], 0
	ds_read_b128 v[190:193], v171 offset:128
	ds_read_b128 v[194:197], v150 offset:128
	s_waitcnt lgkmcnt(6)
	v_mfma_f32_32x32x16_bf16 v[32:47], v[198:201], v[202:205], v[32:47]
	ds_read_b128 v[198:201], v171 offset:160
	ds_read_b128 v[202:205], v150 offset:160
	s_waitcnt lgkmcnt(6)
	v_mfma_f32_32x32x16_bf16 v[32:47], v[210:213], v[214:217], v[32:47]
	ds_read_b128 v[210:213], v171 offset:192
	ds_read_b128 v[214:217], v150 offset:192
	s_waitcnt lgkmcnt(6)
	v_mfma_f32_32x32x16_bf16 v[32:47], v[218:221], v[222:225], v[32:47]
	ds_read_b128 v[218:221], v171 offset:224
	ds_read_b128 v[222:225], v150 offset:224
	s_waitcnt lgkmcnt(6)
	v_mfma_f32_32x32x16_bf16 v[32:47], v[190:193], v[194:197], v[32:47]
	ds_read_b128 v[190:193], v171 offset:256
	ds_read_b128 v[194:197], v150 offset:256
	s_waitcnt lgkmcnt(6)
	v_mfma_f32_32x32x16_bf16 v[32:47], v[198:201], v[202:205], v[32:47]
	ds_read_b128 v[198:201], v171 offset:288
	ds_read_b128 v[202:205], v150 offset:288
	s_waitcnt lgkmcnt(6)
	v_mfma_f32_32x32x16_bf16 v[32:47], v[210:213], v[214:217], v[32:47]
	ds_read_b128 v[210:213], v171 offset:320
	ds_read_b128 v[214:217], v150 offset:320
	s_waitcnt lgkmcnt(6)
	v_mfma_f32_32x32x16_bf16 v[32:47], v[218:221], v[222:225], v[32:47]
	ds_read_b128 v[218:221], v171 offset:352
	ds_read_b128 v[222:225], v150 offset:352
	s_waitcnt lgkmcnt(6)
	v_mfma_f32_32x32x16_bf16 v[32:47], v[190:193], v[194:197], v[32:47]
	ds_read_b128 v[190:193], v171 offset:384
	ds_read_b128 v[194:197], v150 offset:384
	s_waitcnt lgkmcnt(6)
	v_mfma_f32_32x32x16_bf16 v[32:47], v[198:201], v[202:205], v[32:47]
	ds_read_b128 v[198:201], v171 offset:416
	ds_read_b128 v[202:205], v150 offset:416
	s_waitcnt lgkmcnt(6)
	v_mfma_f32_32x32x16_bf16 v[32:47], v[210:213], v[214:217], v[32:47]
	ds_read_b128 v[210:213], v171 offset:448
	ds_read_b128 v[214:217], v150 offset:448
	s_waitcnt lgkmcnt(6)
	v_mfma_f32_32x32x16_bf16 v[32:47], v[218:221], v[222:225], v[32:47]
	ds_read_b128 v[218:221], v171 offset:480
	ds_read_b128 v[222:225], v150 offset:480
	s_waitcnt lgkmcnt(6)
	v_mfma_f32_32x32x16_bf16 v[32:47], v[190:193], v[194:197], v[32:47]
	s_waitcnt lgkmcnt(4)
	v_mfma_f32_32x32x16_bf16 v[32:47], v[198:201], v[202:205], v[32:47]
	s_waitcnt lgkmcnt(2)
	v_mfma_f32_32x32x16_bf16 v[32:47], v[210:213], v[214:217], v[32:47]
	s_waitcnt lgkmcnt(0)
	v_mfma_f32_32x32x16_bf16 v[32:47], v[218:221], v[222:225], v[32:47]
	s_nop 11
	v_pk_mul_f32 v[46:47], v[142:143], v[46:47]
	v_pk_mul_f32 v[44:45], v[140:141], v[44:45]
	v_pk_mul_f32 v[42:43], v[138:139], v[42:43]
	v_pk_mul_f32 v[40:41], v[136:137], v[40:41]
	v_pk_mul_f32 v[38:39], v[134:135], v[38:39]
	v_pk_mul_f32 v[36:37], v[132:133], v[36:37]
	v_pk_mul_f32 v[34:35], v[130:131], v[34:35]
	v_pk_mul_f32 v[32:33], v[108:109], v[32:33]
	s_mov_b64 s[22:23], 0
; #define LAS __attribute__((address_space(3)))
; __device__ __forceinline__ unsigned cvt_pk_bf16(float lo, float hi) { f32x2 v = {lo, hi}; bf16x2_t b = __builtin_convertvector(v, bf16x2_t); return __builtin_bit_cast(unsigned, b); }
; __device__ __forceinline__ void ret_mfma(const Params& P, LAS unsigned char* lds, int wave) {
;     ...
;             if (wave < 4) {
;                 const int mblk = wave >> 1, nblk = wave & 1, n = nblk * 32 + q32;
; #pragma unroll 4
;                 for (int ks = 0; ks < 16; ++ks) {
;                     const bf16x8 a = *(const LAS bf16x8*)(lds + K_OFF + (mblk * 32 + q32) * QP + ks * 32 + hf * 16);
;                     const bf16x8 bq = *(const LAS bf16x8*)(lds + Q_OFF + n * QP + ks * 32 + hf * 16);
;                     acc = __builtin_amdgcn_mfma_f32_32x32x16_bf16(a, bq, acc, 0, 0, 0);
;                 }
; #pragma unroll
;                 for (int i = 0; i < 16; ++i) acc[i] *= dec[i];
; #pragma unroll
;                 for (int j = 0; j < 4; ++j) { u32x2 w; w.x = cvt_pk_bf16(acc[4 * j], acc[4 * j + 1]); w.y = cvt_pk_bf16(acc[4 * j + 2], acc[4 * j + 3]);
;                     *(LAS u32x2*)(lds + S_OFF + n * SP + (mblk * 32 + 8 * j + 4 * hf) * 2) = w; }
.LBB0_261:
	s_and_b64 vcc, exec, s[22:23]
	s_cbranch_vccz .LBB0_265
	ds_read_b128 v[190:193], v172
	ds_read_b128 v[194:197], v150
	ds_read_b128 v[198:201], v172 offset:32
	ds_read_b128 v[202:205], v150 offset:32
	ds_read_b128 v[210:213], v172 offset:64
	ds_read_b128 v[214:217], v150 offset:64
	ds_read_b128 v[218:221], v172 offset:96
	ds_read_b128 v[222:225], v150 offset:96
	s_waitcnt lgkmcnt(6)
	v_mfma_f32_32x32x16_bf16 v[32:47], v[190:193], v[194:197], 0
	ds_read_b128 v[190:193], v172 offset:128
	ds_read_b128 v[194:197], v150 offset:128
	s_waitcnt lgkmcnt(6)
	v_mfma_f32_32x32x16_bf16 v[32:47], v[198:201], v[202:205], v[32:47]
	ds_read_b128 v[198:201], v172 offset:160
	ds_read_b128 v[202:205], v150 offset:160
	s_waitcnt lgkmcnt(6)
	v_mfma_f32_32x32x16_bf16 v[32:47], v[210:213], v[214:217], v[32:47]
	ds_read_b128 v[210:213], v172 offset:192
	ds_read_b128 v[214:217], v150 offset:192
	s_waitcnt lgkmcnt(6)
	v_mfma_f32_32x32x16_bf16 v[32:47], v[218:221], v[222:225], v[32:47]
	ds_read_b128 v[218:221], v172 offset:224
	ds_read_b128 v[222:225], v150 offset:224
	s_waitcnt lgkmcnt(6)
	v_mfma_f32_32x32x16_bf16 v[32:47], v[190:193], v[194:197], v[32:47]
	ds_read_b128 v[190:193], v172 offset:256
	ds_read_b128 v[194:197], v150 offset:256
	s_waitcnt lgkmcnt(6)
	v_mfma_f32_32x32x16_bf16 v[32:47], v[198:201], v[202:205], v[32:47]
	ds_read_b128 v[198:201], v172 offset:288
	ds_read_b128 v[202:205], v150 offset:288
	s_waitcnt lgkmcnt(6)
	v_mfma_f32_32x32x16_bf16 v[32:47], v[210:213], v[214:217], v[32:47]
	ds_read_b128 v[210:213], v172 offset:320
	ds_read_b128 v[214:217], v150 offset:320
	s_waitcnt lgkmcnt(6)
	v_mfma_f32_32x32x16_bf16 v[32:47], v[218:221], v[222:225], v[32:47]
	ds_read_b128 v[218:221], v172 offset:352
	ds_read_b128 v[222:225], v150 offset:352
	s_waitcnt lgkmcnt(6)
	v_mfma_f32_32x32x16_bf16 v[32:47], v[190:193], v[194:197], v[32:47]
	ds_read_b128 v[190:193], v172 offset:384
	ds_read_b128 v[194:197], v150 offset:384
	s_waitcnt lgkmcnt(6)
	v_mfma_f32_32x32x16_bf16 v[32:47], v[198:201], v[202:205], v[32:47]
	ds_read_b128 v[198:201], v172 offset:416
	ds_read_b128 v[202:205], v150 offset:416
	s_waitcnt lgkmcnt(6)
	v_mfma_f32_32x32x16_bf16 v[32:47], v[210:213], v[214:217], v[32:47]
	ds_read_b128 v[210:213], v172 offset:448
	ds_read_b128 v[214:217], v150 offset:448
	s_waitcnt lgkmcnt(6)
	v_mfma_f32_32x32x16_bf16 v[32:47], v[218:221], v[222:225], v[32:47]
	ds_read_b128 v[218:221], v172 offset:480
	ds_read_b128 v[222:225], v150 offset:480
	s_waitcnt lgkmcnt(6)
	v_mfma_f32_32x32x16_bf16 v[32:47], v[190:193], v[194:197], v[32:47]
	s_waitcnt lgkmcnt(4)
	v_mfma_f32_32x32x16_bf16 v[32:47], v[198:201], v[202:205], v[32:47]
	s_waitcnt lgkmcnt(2)
	v_mfma_f32_32x32x16_bf16 v[32:47], v[210:213], v[214:217], v[32:47]
	s_waitcnt lgkmcnt(0)
	v_mfma_f32_32x32x16_bf16 v[32:47], v[218:221], v[222:225], v[32:47]
	s_nop 11
	v_pk_mul_f32 v[32:33], v[104:105], v[32:33]
	v_pk_mul_f32 v[34:35], v[110:111], v[34:35]
	v_pk_mul_f32 v[36:37], v[112:113], v[36:37]
	v_pk_mul_f32 v[38:39], v[114:115], v[38:39]
	v_pk_mul_f32 v[40:41], v[116:117], v[40:41]
	v_pk_mul_f32 v[42:43], v[118:119], v[42:43]
	v_pk_mul_f32 v[44:45], v[120:121], v[44:45]
	v_pk_mul_f32 v[46:47], v[122:123], v[46:47]
	v_cvt_pk_bf16_f32 v146, v32, v33
	v_cvt_pk_bf16_f32 v147, v34, v35
	v_cvt_pk_bf16_f32 v190, v36, v37
	v_cvt_pk_bf16_f32 v191, v38, v39
	ds_write2_b64 v178, v[146:147], v[190:191] offset1:2
	v_cvt_pk_bf16_f32 v146, v40, v41
	v_cvt_pk_bf16_f32 v147, v42, v43
	v_cvt_pk_bf16_f32 v190, v44, v45
	v_cvt_pk_bf16_f32 v191, v46, v47
	ds_write2_b64 v178, v[146:147], v[190:191] offset0:4 offset1:6
